# merge: 3 of the 8 second-half running-sum groups kept in 24 KB of extra static LDS across the K segments (static LDS 28672 B; total LDS = 160 KB)
# speedup vs baseline: 1.0077x; 1.0077x over previous
.Lmrs_st_end:
	s_mov_b32 s87, 0x21000
	v_lshl_add_u32 v254, v197, 4, s87
	v_lshlrev_b32_e32 v0, 4, v14
	v_add_u32_e32 v1, 0x2000, v0
	v_ashrrev_i32_e32 v2, 31, v1
	v_lshrrev_b32_e32 v2, 22, v2
	v_add_u32_e32 v2, v1, v2
	v_ashrrev_i32_e32 v8, 10, v2
	v_mul_i32_i24_e32 v3, 0x400, v8
	v_sub_u32_e32 v1, v1, v3
	v_lshrrev_b32_e32 v3, 4, v1
	v_bitop3_b32 v1, v3, v1, 32 bitop3:0x6c
	v_ashrrev_i32_e32 v3, 31, v1
	v_lshrrev_b32_e32 v3, 26, v3
	v_add_u32_e32 v3, v1, v3
	v_ashrrev_i32_e32 v9, 6, v3
	v_and_b32_e32 v3, 0xc0, v3
	v_sub_u32_e32 v1, v1, v3
	v_lshlrev_b32_e32 v2, 5, v8
	v_ashrrev_i16_sdwa v1, v221, sext(v1) dst_sel:DWORD dst_unused:UNUSED_PAD src0_sel:DWORD src1_sel:BYTE_0
	v_and_b32_e32 v2, 32, v2
	v_bfe_i32 v10, v1, 0, 16
	v_add_u32_e32 v1, v2, v10
	v_lshlrev_b32_e32 v2, 3, v8
	v_and_b32_e32 v2, 0x1ffff0, v2
	v_add_lshl_u32 v2, v9, v2, 11
	v_lshl_add_u32 v204, v1, 1, v2
	v_bfe_i32 v2, v14, 27, 1
	v_lshrrev_b32_e32 v2, 22, v2
	v_add_u32_e32 v2, v0, v2
	v_and_b32_e32 v2, 0xfffffc00, v2
	s_add_u32 s3, s96, s0
	v_sub_u32_e32 v0, v0, v2
	s_addc_u32 s18, s97, s1
	v_lshrrev_b32_e32 v2, 4, v0
	s_add_u32 s19, s3, 0xd000000
	v_bitop3_b32 v2, v2, v0, 32 bitop3:0x6c
	v_ashrrev_i32_e32 v0, 31, v0
	s_addc_u32 s20, s18, 0
	s_lshl_b32 s0, s50, 21
	v_lshrrev_b32_e32 v0, 26, v0
	s_add_u32 s0, s3, s0
	v_ashrrev_i32_e32 v1, 31, v14
	v_add_u32_e32 v0, v2, v0
	s_addc_u32 s1, s18, 0
	v_lshrrev_b32_e32 v1, 26, v1
	v_ashrrev_i32_e32 v12, 6, v0
	s_add_u32 s21, s0, 0x10100000
	v_add_u32_e32 v1, v14, v1
	v_mul_i32_i24_e32 v0, 64, v12
	s_addc_u32 s22, s1, 0
	s_ashr_i32 s6, s2, 6
	v_ashrrev_i32_e32 v11, 6, v1
	v_sub_u32_e32 v0, v2, v0
	s_ashr_i32 s7, s2, 8
	s_lshl_b32 s23, s6, 10
	v_lshlrev_b32_e32 v1, 5, v11
	v_ashrrev_i16_sdwa v0, v221, sext(v0) dst_sel:DWORD dst_unused:UNUSED_PAD src0_sel:DWORD src1_sel:BYTE_0
	s_add_u32 s8, s19, s65
	v_and_b32_e32 v1, 32, v1
	v_bfe_i32 v13, v0, 0, 16
	s_addc_u32 s9, s20, 0
	v_add_u32_e32 v0, v1, v13
	v_lshlrev_b32_e32 v1, 3, v11
	s_add_u32 s14, s21, s66
	v_and_b32_e32 v1, 0x1ffff0, v1
	s_addc_u32 s15, s22, 0
	v_add_lshl_u32 v1, v12, v1, 11
	s_add_i32 s24, s23, 0
	v_lshl_add_u32 v194, v0, 1, v1
	s_add_i32 m0, s24, 0x10000
	s_add_i32 s25, s24, 0x2000
	global_load_lds_dwordx4 v194, s[14:15]
	s_add_i32 m0, s24, 0x12000
	s_add_u32 s0, s14, 0x40000
	global_load_lds_dwordx4 v204, s[14:15]
	s_mov_b32 m0, s24
	s_addc_u32 s1, s15, 0
	global_load_lds_dwordx4 v194, s[8:9]
	s_mov_b32 m0, s25
	v_mov_b32_e32 v205, v195
	global_load_lds_dwordx4 v204, s[8:9]
	s_add_i32 m0, s24, 0x14000
	v_lshl_add_u64 v[6:7], s[14:15], 0, v[194:195]
	global_load_lds_dwordx4 v194, s[0:1]
	s_add_i32 m0, s24, 0x16000
	v_lshl_add_u64 v[4:5], s[14:15], 0, v[204:205]
	global_load_lds_dwordx4 v204, s[0:1]
	s_add_u32 s0, s8, 0x40000
	s_addc_u32 s1, s9, 0
	s_add_i32 s26, s24, 0x4000
	s_mov_b32 m0, s26
	s_add_i32 s27, s24, 0x6000
	global_load_lds_dwordx4 v194, s[0:1]
	s_mov_b32 m0, s27
	v_lshl_add_u64 v[2:3], s[8:9], 0, v[194:195]
	global_load_lds_dwordx4 v204, s[0:1]
	s_cmp_lg_u32 s7, 1
	v_lshl_add_u64 v[0:1], s[8:9], 0, v[204:205]
	s_cbranch_scc1 .LBB0_664
	s_barrier

.LBB0_666:
	s_waitcnt vmcnt(0) lgkmcnt(0)
	v_lshlrev_b32_e32 v132, 16, v128
	v_lshlrev_b32_e32 v133, 16, v120
	v_fmac_f32_e32 v132, v60, v133
	v_and_b32_e32 v60, 0xffff0000, v128
	v_and_b32_e32 v120, 0xffff0000, v120
	v_fmac_f32_e32 v60, v61, v120
	v_lshlrev_b32_e32 v61, 16, v129
	v_lshlrev_b32_e32 v120, 16, v121
	v_fmac_f32_e32 v61, v62, v120
	v_and_b32_e32 v62, 0xffff0000, v129
	v_and_b32_e32 v120, 0xffff0000, v121
	v_fmac_f32_e32 v62, v63, v120
	v_cvt_pk_bf16_f32 v60, v132, v60
	v_cvt_pk_bf16_f32 v61, v61, v62
	v_lshlrev_b32_e32 v62, 16, v130
	v_lshlrev_b32_e32 v63, 16, v122
	v_fmac_f32_e32 v62, v56, v63
	v_and_b32_e32 v56, 0xffff0000, v130
	v_and_b32_e32 v63, 0xffff0000, v122
	v_fmac_f32_e32 v56, v57, v63
	v_cvt_pk_bf16_f32 v62, v62, v56
	v_lshlrev_b32_e32 v56, 16, v131
	v_lshlrev_b32_e32 v57, 16, v123
	v_fmac_f32_e32 v56, v58, v57
	v_and_b32_e32 v57, 0xffff0000, v131
	v_and_b32_e32 v58, 0xffff0000, v123
	v_fmac_f32_e32 v57, v59, v58
	v_lshlrev_b32_e32 v58, 16, v116
	v_lshlrev_b32_e32 v59, 16, v112
	v_fmac_f32_e32 v58, v52, v59
	v_and_b32_e32 v52, 0xffff0000, v116
	v_and_b32_e32 v59, 0xffff0000, v112
	v_cvt_pk_bf16_f32 v63, v56, v57
	v_lshl_add_u64 v[56:57], v[126:127], 0, v[124:125]
	v_fmac_f32_e32 v52, v53, v59
	ds_write_b128 v254, v[60:63] offset:0
	s_cmp_lg_u32 s37, 2
	s_cbranch_scc1 .Lmls_0
	global_store_dwordx4 v[56:57], v[60:63], off
.Lmls_0:
	v_cvt_pk_bf16_f32 v52, v58, v52
	v_lshlrev_b32_e32 v53, 16, v117
	v_lshlrev_b32_e32 v58, 16, v113
	v_fmac_f32_e32 v53, v54, v58
	v_and_b32_e32 v54, 0xffff0000, v117
	v_and_b32_e32 v58, 0xffff0000, v113
	v_fmac_f32_e32 v54, v55, v58
	v_cvt_pk_bf16_f32 v53, v53, v54
	v_lshlrev_b32_e32 v54, 16, v118
	v_lshlrev_b32_e32 v55, 16, v114
	v_fmac_f32_e32 v54, v44, v55
	v_and_b32_e32 v44, 0xffff0000, v118
	v_and_b32_e32 v55, 0xffff0000, v114
	v_fmac_f32_e32 v44, v45, v55
	v_cvt_pk_bf16_f32 v54, v54, v44
	v_lshlrev_b32_e32 v44, 16, v119
	v_lshlrev_b32_e32 v45, 16, v115
	v_fmac_f32_e32 v44, v46, v45
	v_and_b32_e32 v45, 0xffff0000, v119
	v_and_b32_e32 v46, 0xffff0000, v115
	v_fmac_f32_e32 v45, v47, v46
	v_cvt_pk_bf16_f32 v55, v44, v45
	v_lshlrev_b32_e32 v44, 16, v96
	v_lshlrev_b32_e32 v45, 16, v108
	v_fmac_f32_e32 v44, v48, v45
	v_and_b32_e32 v45, 0xffff0000, v96
	v_and_b32_e32 v46, 0xffff0000, v108
	v_fmac_f32_e32 v45, v49, v46
	ds_write_b128 v254, v[52:55] offset:8192
	s_cmp_lg_u32 s37, 2
	s_cbranch_scc1 .Lmls_1
	global_store_dwordx4 v[56:57], v[52:55], off offset:256
.Lmls_1:
	v_cvt_pk_bf16_f32 v44, v44, v45
	v_lshlrev_b32_e32 v45, 16, v97
	v_lshlrev_b32_e32 v46, 16, v109
	v_fmac_f32_e32 v45, v50, v46
	v_and_b32_e32 v46, 0xffff0000, v97
	v_and_b32_e32 v47, 0xffff0000, v109
	v_fmac_f32_e32 v46, v51, v47
	v_cvt_pk_bf16_f32 v45, v45, v46
	v_lshlrev_b32_e32 v46, 16, v98
	v_lshlrev_b32_e32 v47, 16, v110
	v_fmac_f32_e32 v46, v40, v47
	v_and_b32_e32 v40, 0xffff0000, v98
	v_and_b32_e32 v47, 0xffff0000, v110
	v_fmac_f32_e32 v40, v41, v47
	v_cvt_pk_bf16_f32 v46, v46, v40
	v_lshlrev_b32_e32 v40, 16, v99
	v_lshlrev_b32_e32 v41, 16, v111
	v_add_u32_e32 v52, 0x90, v210
	v_fmac_f32_e32 v40, v42, v41
	v_and_b32_e32 v41, 0xffff0000, v99
	v_and_b32_e32 v42, 0xffff0000, v111
	v_fmac_f32_e32 v41, v43, v42
	v_ashrrev_i32_e32 v53, 31, v52
	v_cvt_pk_bf16_f32 v47, v40, v41
	v_lshlrev_b64 v[40:41], 11, v[52:53]
	v_lshlrev_b32_e32 v42, 16, v104
	v_lshlrev_b32_e32 v43, 16, v100
	v_lshl_add_u64 v[40:41], s[0:1], 0, v[40:41]
	v_fmac_f32_e32 v42, v36, v43
	v_and_b32_e32 v36, 0xffff0000, v104
	v_and_b32_e32 v43, 0xffff0000, v100
	v_lshl_add_u64 v[40:41], v[40:41], 0, v[124:125]
	v_fmac_f32_e32 v36, v37, v43
	ds_write_b128 v254, v[44:47] offset:16384
	s_cmp_lg_u32 s37, 2
	s_cbranch_scc1 .Lmls_2
	global_store_dwordx4 v[40:41], v[44:47], off
.Lmls_2:
	v_cvt_pk_bf16_f32 v36, v42, v36
	v_lshlrev_b32_e32 v37, 16, v105
	v_lshlrev_b32_e32 v42, 16, v101
	v_fmac_f32_e32 v37, v38, v42
	v_and_b32_e32 v38, 0xffff0000, v105
	v_and_b32_e32 v42, 0xffff0000, v101
	v_fmac_f32_e32 v38, v39, v42
	v_cvt_pk_bf16_f32 v37, v37, v38
	v_lshlrev_b32_e32 v38, 16, v106
	v_lshlrev_b32_e32 v39, 16, v102
	v_fmac_f32_e32 v38, v28, v39
	v_and_b32_e32 v28, 0xffff0000, v106
	v_and_b32_e32 v39, 0xffff0000, v102
	v_fmac_f32_e32 v28, v29, v39
	v_cvt_pk_bf16_f32 v38, v38, v28
	v_lshlrev_b32_e32 v28, 16, v107
	v_lshlrev_b32_e32 v29, 16, v103
	v_fmac_f32_e32 v28, v30, v29
	v_and_b32_e32 v29, 0xffff0000, v107
	v_and_b32_e32 v30, 0xffff0000, v103
	v_fmac_f32_e32 v29, v31, v30
	v_cvt_pk_bf16_f32 v39, v28, v29
	v_lshlrev_b32_e32 v28, 16, v80
	v_lshlrev_b32_e32 v29, 16, v92
	v_fmac_f32_e32 v28, v32, v29
	v_and_b32_e32 v29, 0xffff0000, v80
	v_and_b32_e32 v30, 0xffff0000, v92
	v_fmac_f32_e32 v29, v33, v30
	global_store_dwordx4 v[40:41], v[36:39], off offset:256
	v_cvt_pk_bf16_f32 v28, v28, v29
	v_lshlrev_b32_e32 v29, 16, v81
	v_lshlrev_b32_e32 v30, 16, v93
	v_fmac_f32_e32 v29, v34, v30
	v_and_b32_e32 v30, 0xffff0000, v81
	v_and_b32_e32 v31, 0xffff0000, v93
	v_fmac_f32_e32 v30, v35, v31
	v_cvt_pk_bf16_f32 v29, v29, v30
	v_lshlrev_b32_e32 v30, 16, v82
	v_lshlrev_b32_e32 v31, 16, v94
	v_fmac_f32_e32 v30, v24, v31
	v_and_b32_e32 v24, 0xffff0000, v82
	v_and_b32_e32 v31, 0xffff0000, v94
	v_fmac_f32_e32 v24, v25, v31
	v_cvt_pk_bf16_f32 v30, v30, v24
	v_lshlrev_b32_e32 v24, 16, v83
	v_lshlrev_b32_e32 v25, 16, v95
	v_add_u32_e32 v36, 0xa0, v210
	v_fmac_f32_e32 v24, v26, v25
	v_and_b32_e32 v25, 0xffff0000, v83
	v_and_b32_e32 v26, 0xffff0000, v95
	v_fmac_f32_e32 v25, v27, v26
	v_ashrrev_i32_e32 v37, 31, v36
	v_cvt_pk_bf16_f32 v31, v24, v25
	v_lshlrev_b64 v[24:25], 11, v[36:37]
	v_lshlrev_b32_e32 v26, 16, v88
	v_lshlrev_b32_e32 v27, 16, v84
	v_lshl_add_u64 v[24:25], s[0:1], 0, v[24:25]
	v_fmac_f32_e32 v26, v20, v27
	v_and_b32_e32 v20, 0xffff0000, v88
	v_and_b32_e32 v27, 0xffff0000, v84
	v_lshl_add_u64 v[24:25], v[24:25], 0, v[124:125]
	v_fmac_f32_e32 v20, v21, v27
	global_store_dwordx4 v[24:25], v[28:31], off
	v_cvt_pk_bf16_f32 v20, v26, v20
	v_lshlrev_b32_e32 v21, 16, v89
	v_lshlrev_b32_e32 v26, 16, v85
	v_fmac_f32_e32 v21, v22, v26
	v_and_b32_e32 v22, 0xffff0000, v89
	v_and_b32_e32 v26, 0xffff0000, v85
	v_fmac_f32_e32 v22, v23, v26
	v_cvt_pk_bf16_f32 v21, v21, v22
	v_lshlrev_b32_e32 v22, 16, v90
	v_lshlrev_b32_e32 v23, 16, v86
	v_fmac_f32_e32 v22, v12, v23
	v_and_b32_e32 v12, 0xffff0000, v90
	v_and_b32_e32 v23, 0xffff0000, v86
	v_fmac_f32_e32 v12, v13, v23
	v_cvt_pk_bf16_f32 v22, v22, v12
	v_lshlrev_b32_e32 v12, 16, v91
	v_lshlrev_b32_e32 v13, 16, v87
	v_fmac_f32_e32 v12, v14, v13
	v_and_b32_e32 v13, 0xffff0000, v91
	v_and_b32_e32 v14, 0xffff0000, v87
	v_fmac_f32_e32 v13, v15, v14
	v_cvt_pk_bf16_f32 v23, v12, v13
	v_lshlrev_b32_e32 v12, 16, v64
	v_lshlrev_b32_e32 v13, 16, v76
	v_fmac_f32_e32 v12, v16, v13
	v_and_b32_e32 v13, 0xffff0000, v64
	v_and_b32_e32 v14, 0xffff0000, v76
	v_fmac_f32_e32 v13, v17, v14
	global_store_dwordx4 v[24:25], v[20:23], off offset:256
	v_cvt_pk_bf16_f32 v12, v12, v13
	v_lshlrev_b32_e32 v13, 16, v65
	v_lshlrev_b32_e32 v14, 16, v77
	v_fmac_f32_e32 v13, v18, v14
	v_and_b32_e32 v14, 0xffff0000, v65
	v_and_b32_e32 v15, 0xffff0000, v77
	v_fmac_f32_e32 v14, v19, v15
	v_cvt_pk_bf16_f32 v13, v13, v14
	v_lshlrev_b32_e32 v14, 16, v66
	v_lshlrev_b32_e32 v15, 16, v78
	v_fmac_f32_e32 v14, v8, v15
	v_and_b32_e32 v8, 0xffff0000, v66
	v_and_b32_e32 v15, 0xffff0000, v78
	v_fmac_f32_e32 v8, v9, v15
	v_cvt_pk_bf16_f32 v14, v14, v8
	v_lshlrev_b32_e32 v8, 16, v67
	v_lshlrev_b32_e32 v9, 16, v79
	v_add_u32_e32 v20, 0xb0, v210
	v_fmac_f32_e32 v8, v10, v9
	v_and_b32_e32 v9, 0xffff0000, v67
	v_and_b32_e32 v10, 0xffff0000, v79
	v_fmac_f32_e32 v9, v11, v10
	v_ashrrev_i32_e32 v21, 31, v20
	v_cvt_pk_bf16_f32 v15, v8, v9
	v_lshlrev_b64 v[8:9], 11, v[20:21]
	v_lshlrev_b32_e32 v10, 16, v72
	v_lshlrev_b32_e32 v11, 16, v68
	v_lshl_add_u64 v[8:9], s[0:1], 0, v[8:9]
	v_fmac_f32_e32 v10, v4, v11
	v_and_b32_e32 v4, 0xffff0000, v72
	v_and_b32_e32 v11, 0xffff0000, v68
	v_lshl_add_u64 v[8:9], v[8:9], 0, v[124:125]
	v_fmac_f32_e32 v4, v5, v11
	global_store_dwordx4 v[8:9], v[12:15], off
	v_cvt_pk_bf16_f32 v4, v10, v4
	v_lshlrev_b32_e32 v5, 16, v73
	v_lshlrev_b32_e32 v10, 16, v69
	v_fmac_f32_e32 v5, v6, v10
	v_and_b32_e32 v6, 0xffff0000, v73
	v_and_b32_e32 v10, 0xffff0000, v69
	v_fmac_f32_e32 v6, v7, v10
	v_cvt_pk_bf16_f32 v5, v5, v6
	v_lshlrev_b32_e32 v6, 16, v74
	v_lshlrev_b32_e32 v7, 16, v70
	v_fmac_f32_e32 v6, v0, v7
	v_and_b32_e32 v0, 0xffff0000, v74
	v_and_b32_e32 v7, 0xffff0000, v70
	v_fmac_f32_e32 v0, v1, v7
	v_cvt_pk_bf16_f32 v6, v6, v0
	v_lshlrev_b32_e32 v0, 16, v75
	v_lshlrev_b32_e32 v1, 16, v71
	v_fmac_f32_e32 v0, v2, v1
	v_and_b32_e32 v1, 0xffff0000, v75
	v_and_b32_e32 v2, 0xffff0000, v71
	s_and_b64 vcc, exec, s[6:7]
	s_mov_b32 s37, s30
	s_mov_b32 s38, s34
	s_mov_b32 s39, s35
	s_mov_b32 s40, s36
	s_mov_b64 s[14:15], s[12:13]
	s_mov_b64 s[8:9], s[10:11]
	v_fmac_f32_e32 v1, v3, v2
	v_cvt_pk_bf16_f32 v7, v0, v1
	global_store_dwordx4 v[8:9], v[4:7], off offset:256
	s_waitcnt lgkmcnt(0)
	s_cbranch_vccnz .LBB0_704

.Lmrs_7:
	s_cbranch_vccnz .LBB0_690
	ds_read_b128 v[128:131], v254 offset:0
.LBB0_690:
	global_load_dwordx4 v[112:115], v[68:69], off offset:256
	v_mov_b32_e32 v96, 0
	s_and_b64 vcc, exec, s[8:9]
	v_mov_b32_e32 v116, 0
	v_mov_b32_e32 v117, 0
	v_mov_b32_e32 v118, 0
	v_mov_b32_e32 v119, 0
	s_cbranch_vccnz .LBB0_692
	ds_read_b128 v[116:119], v254 offset:8192
.LBB0_692:
	v_or_b32_e32 v64, 16, v66
	v_mov_b64_e32 v[68:69], s[14:15]
	v_mad_i64_i32 v[68:69], s[16:17], v64, s81, v[68:69]
	v_lshl_add_u64 v[68:69], v[212:213], 1, v[68:69]
	global_load_dwordx4 v[108:111], v[68:69], off
	v_ashrrev_i32_e32 v65, 31, v64
	v_lshlrev_b64 v[64:65], 11, v[64:65]
	v_lshl_add_u64 v[64:65], s[0:1], 0, v[64:65]
	s_and_b64 vcc, exec, s[8:9]
	v_lshl_add_u64 v[64:65], v[212:213], 1, v[64:65]
	v_mov_b32_e32 v97, 0
	v_mov_b32_e32 v98, 0
	v_mov_b32_e32 v99, 0
	s_cbranch_vccnz .LBB0_694
	ds_read_b128 v[96:99], v254 offset:16384

.Lmrs_ld_end:
	v_readlane_b32 s88, v253, 24
	v_readlane_b32 s89, v253, 25
	v_mov_b32_e32 v254, 0
	s_nop 4
	global_load_dword v254, v254, s[88:89] sc1

	.amdhsa_kernel _Z10mk_forward6Params
		.amdhsa_group_segment_fixed_size 28672
		.amdhsa_private_segment_fixed_size 0
		.amdhsa_kernarg_size 376
		.amdhsa_user_sgpr_count 2
		.amdhsa_user_sgpr_dispatch_ptr 0
		.amdhsa_user_sgpr_queue_ptr 0
		.amdhsa_user_sgpr_kernarg_segment_ptr 1
		.amdhsa_user_sgpr_dispatch_id 0
		.amdhsa_user_sgpr_kernarg_preload_length 0
		.amdhsa_user_sgpr_kernarg_preload_offset 0
		.amdhsa_user_sgpr_private_segment_size 0
		.amdhsa_uses_dynamic_stack 0
		.amdhsa_enable_private_segment 0
		.amdhsa_system_sgpr_workgroup_id_x 1
		.amdhsa_system_sgpr_workgroup_id_y 0
		.amdhsa_system_sgpr_workgroup_id_z 0
		.amdhsa_system_sgpr_workgroup_info 0
		.amdhsa_system_vgpr_workitem_id 2
		.amdhsa_next_free_vgpr 256
		.amdhsa_next_free_sgpr 100
		.amdhsa_accum_offset 256
		.amdhsa_reserve_vcc 1
		.amdhsa_float_round_mode_32 0
		.amdhsa_float_round_mode_16_64 0
		.amdhsa_float_denorm_mode_32 3
		.amdhsa_float_denorm_mode_16_64 3
		.amdhsa_dx10_clamp 1
		.amdhsa_ieee_mode 1
		.amdhsa_fp16_overflow 0
		.amdhsa_tg_split 0
		.amdhsa_exception_fp_ieee_invalid_op 0
		.amdhsa_exception_fp_denorm_src 0
		.amdhsa_exception_fp_ieee_div_zero 0
		.amdhsa_exception_fp_ieee_overflow 0
		.amdhsa_exception_fp_ieee_underflow 0
		.amdhsa_exception_fp_ieee_inexact 0
		.amdhsa_exception_int_div_zero 0
	.end_amdhsa_kernel

amdhsa.kernels:
  - .agpr_count:     0
    .args:
      - .offset:         0
        .size:           120
        .value_kind:     by_value
      - .offset:         120
        .size:           4
        .value_kind:     hidden_block_count_x
      - .offset:         124
        .size:           4
        .value_kind:     hidden_block_count_y
      - .offset:         128
        .size:           4
        .value_kind:     hidden_block_count_z
      - .offset:         132
        .size:           2
        .value_kind:     hidden_group_size_x
      - .offset:         134
        .size:           2
        .value_kind:     hidden_group_size_y
      - .offset:         136
        .size:           2
        .value_kind:     hidden_group_size_z
      - .offset:         138
        .size:           2
        .value_kind:     hidden_remainder_x
      - .offset:         140
        .size:           2
        .value_kind:     hidden_remainder_y
      - .offset:         142
        .size:           2
        .value_kind:     hidden_remainder_z
      - .offset:         160
        .size:           8
        .value_kind:     hidden_global_offset_x
      - .offset:         168
        .size:           8
        .value_kind:     hidden_global_offset_y
      - .offset:         176
        .size:           8
        .value_kind:     hidden_global_offset_z
      - .offset:         184
        .size:           2
        .value_kind:     hidden_grid_dims
      - .offset:         208
        .size:           8
        .value_kind:     hidden_multigrid_sync_arg
      - .offset:         240
        .size:           4
        .value_kind:     hidden_dynamic_lds_size
    .group_segment_fixed_size: 28672
    .kernarg_segment_align: 8
    .kernarg_segment_size: 376
    .language:       OpenCL C
    .language_version:
      - 2
      - 0
    .max_flat_workgroup_size: 512
    .name:           _Z10mk_forward6Params
    .private_segment_fixed_size: 0
    .sgpr_count:     106
    .sgpr_spill_count: 106
    .symbol:         _Z10mk_forward6Params.kd
    .uniform_work_group_size: 1
    .uses_dynamic_stack: false
    .vgpr_count:     256
    .vgpr_spill_count: 0
    .wavefront_size: 64
